# GEMM1: per-XCD rotation of N-tile order (pn+3*xcd mod 23) to de-phase store bursts across XCDs; on top of attention prio/issue edits and peeled zero-free K-loops
# speedup vs baseline: 1.0189x; 1.0024x over previous
;     __host__ __device__ bool next(int i, Unit& u) const {
;         const long L = (long)i * G + c; if (L >= nwg) return false;
;         int wgid = (int)L; { const int q = nwg / NXCD, r = nwg % NXCD, xcd = wgid % NXCD, off = wgid / NXCD; wgid = (xcd < r ? xcd * (q + 1) : r * (q + 1) + (xcd - r) * q) + off; }
;         const int nig = WGM * nN, gid = wgid / nig, fm = gid * WGM, gsz = (nM - fm) < WGM ? (nM - fm) : WGM;
;         u.pm = fm + ((wgid % nig) % gsz); u.pn = (wgid % nig) / gsz; return true;
.LBB0_339:
	s_cmp_lt_i32 s92, 3
	s_cselect_b64 s[2:3], -1, 0
	s_and_b64 s[0:1], s[2:3], s[0:1]
	s_andn2_b64 vcc, exec, s[0:1]
	s_mov_b64 s[0:1], s[48:49]
	s_mov_b64 s[14:15], s[62:63]
	v_writelane_b32 v254, s0, 23
	s_nop 1
	v_writelane_b32 v254, s1, 24
	v_writelane_b32 v254, s2, 25
	v_writelane_b32 v254, s3, 26
	v_writelane_b32 v254, s4, 27
	v_writelane_b32 v254, s5, 28
	v_writelane_b32 v254, s6, 29
	v_writelane_b32 v254, s7, 30
	v_writelane_b32 v254, s8, 31
	v_writelane_b32 v254, s9, 32
	v_writelane_b32 v254, s10, 33
	v_writelane_b32 v254, s11, 34
	v_writelane_b32 v254, s12, 35
	v_writelane_b32 v254, s13, 36
	v_writelane_b32 v254, s14, 37
	v_writelane_b32 v254, s15, 38
	s_cbranch_vccnz .LBB0_1057
	s_cmpk_lt_i32 s80, 0xb80
	v_readfirstlane_b32 s11, v200
	s_movk_i32 s0, 0x400
	s_cselect_b64 s[2:3], -1, 0
	s_cmpk_gt_i32 s80, 0xb7f
	s_cbranch_scc1 .LBB0_342
	s_ashr_i32 s1, s80, 31
	s_lshr_b32 s1, s1, 29
	s_add_i32 s1, s80, s1
	s_ashr_i32 s4, s1, 3
	s_and_b32 s1, s1, -8
	s_sub_i32 s1, s80, s1
	s_cmp_lt_i32 s1, 0
	s_movk_i32 s5, 0x171
	s_cselect_b32 s5, s5, 0x170
	s_mul_i32 s1, s1, s5
	s_add_i32 s1, s1, s4
	s_mul_hi_i32 s4, s1, 0xb21642c9
	s_add_i32 s4, s4, s1
	s_lshr_b32 s5, s4, 31
	s_ashr_i32 s4, s4, 7
	s_add_i32 s4, s4, s5
	s_lshl_b32 s5, s4, 3
	s_mulk_i32 s4, 0xb8
	s_sub_i32 s1, s1, s4
	s_sext_i32_i16 s4, s1
	s_bfe_u32 s4, s4, 0x3001c
	s_add_i32 s4, s1, s4
	s_sext_i32_i16 s6, s4
	s_and_b32 s4, s4, 0xfff8
	s_sub_i32 s1, s1, s4
	s_sext_i32_i16 s1, s1
	s_add_i32 s33, s5, s1
	s_ashr_i32 s10, s6, 3
	s_and_b32 s32, s80, 7
	s_mul_i32 s32, s32, 3
	s_add_i32 s10, s10, s32
	s_sub_i32 s1, s10, 23
	s_cmp_ge_i32 s10, 23
	s_cselect_b32 s10, s1, s10

;     __host__ __device__ bool next(int i, Unit& u) const {
;         const long L = (long)i * G + c; if (L >= nwg) return false;
;         int wgid = (int)L; { const int q = nwg / NXCD, r = nwg % NXCD, xcd = wgid % NXCD, off = wgid / NXCD; wgid = (xcd < r ? xcd * (q + 1) : r * (q + 1) + (xcd - r) * q) + off; }
;         const int nig = WGM * nN, gid = wgid / nig, fm = gid * WGM, gsz = (nM - fm) < WGM ? (nM - fm) : WGM;
;         u.pm = fm + ((wgid % nig) % gsz); u.pn = (wgid % nig) / gsz; return true;
; template <class Epi, class Sched, bool ALIGN_EPI = false, bool SP2 = false>
; __device__ __forceinline__ void gemm_phase(PG8_LAS unsigned char* lds, const Gemm g, const Sched& S, const Epi& E) {
;     ...
;         const bool has_next = S.next(ui + 1, nxt);
;         const char* nA = has_next ? (const char*)g.A + (size_t)nxt.pm * tstep : cA; const char* nB = has_next ? (const char*)g.Bt + (size_t)nxt.pn * tstep : cB;
.LBB0_348:
	s_add_i32 s79, s79, 1
	s_mul_i32 s0, s79, s73
	s_mul_hi_u32 s1, s79, s83
	s_add_i32 s1, s1, s0
	s_mul_i32 s0, s79, s83
	s_add_u32 s2, s0, s86
	s_addc_u32 s3, s1, s74
	v_cmp_gt_i64_e32 vcc, s[2:3], v[144:145]
	v_cmp_lt_i64_e64 s[0:1], s[2:3], v[142:143]
	s_cbranch_vccnz .LBB0_350
	s_ashr_i32 s3, s2, 31
	s_lshr_b32 s3, s3, 29
	s_add_i32 s3, s2, s3
	s_ashr_i32 s11, s3, 3
	s_and_b32 s3, s3, -8
	s_sub_i32 s2, s2, s3
	s_cmp_lt_i32 s2, 0
	s_movk_i32 s3, 0x171
	s_cselect_b32 s3, s3, 0x170
	s_mul_i32 s2, s2, s3
	s_add_i32 s2, s2, s11
	s_mul_hi_i32 s3, s2, 0xb21642c9
	s_add_i32 s3, s3, s2
	s_lshr_b32 s11, s3, 31
	s_ashr_i32 s3, s3, 7
	s_add_i32 s3, s3, s11
	s_lshl_b32 s11, s3, 3
	s_sub_i32 s16, 0x80, s11
	s_min_i32 s16, s16, 8
	s_abs_i32 s44, s16
	v_cvt_f32_u32_e32 v0, s44
	s_sub_i32 s46, 0, s44
	s_mulk_i32 s3, 0xb8
	s_sub_i32 s2, s2, s3
	v_rcp_iflag_f32_e32 v0, v0
	s_abs_i32 s3, s2
	s_xor_b32 s45, s2, s16
	s_ashr_i32 s45, s45, 31
	v_mul_f32_e32 v0, 0x4f7ffffe, v0
	v_cvt_u32_f32_e32 v0, v0
	s_nop 0
	v_readfirstlane_b32 s47, v0
	s_mul_i32 s46, s46, s47
	s_mul_hi_u32 s46, s47, s46
	s_add_i32 s47, s47, s46
	s_mul_hi_u32 s46, s3, s47
	s_mul_i32 s47, s46, s44
	s_sub_i32 s3, s3, s47
	s_add_i32 s48, s46, 1
	s_sub_i32 s47, s3, s44
	s_cmp_ge_u32 s3, s44
	s_cselect_b32 s46, s48, s46
	s_cselect_b32 s3, s47, s3
	s_add_i32 s47, s46, 1
	s_cmp_ge_u32 s3, s44
	s_cselect_b32 s3, s47, s46
	s_xor_b32 s3, s3, s45
	s_sub_i32 s80, s3, s45
	s_mul_i32 s3, s80, s16
	s_sub_i32 s2, s2, s3
	s_add_i32 s81, s11, s2
	s_add_i32 s80, s80, s32
	s_sub_i32 s2, s80, 23
	s_cmp_ge_i32 s80, 23
	s_cselect_b32 s80, s2, s80

; #define LAS __attribute__((address_space(3)))
; __device__ __forceinline__ void attn_phase(const Ptrs& P, LAS unsigned char* lds, int vcu) {
;     ...
;         for (int t = 0; t < NT; ++t) {
;             asm volatile("s_waitcnt vmcnt(0)" ::: "memory");
;             __syncthreads();
;             if (t + 1 < NT) ISSUE_TILE(t + 1, (t + 1) & 1); else if (ui + 1 < 4) ISSUE_TILE(0, 0);
;             if (64 * t <= qw) {
;                 LAS const unsigned char* st = lds + (t & 1) * ATT_STAGE;
;                 f32x16 p0, p1;
;     ...
;                 { constexpr int PD = 4;
;                   bf16x8 ka[12], kb[12];
; #pragma unroll
;                   for (int ks = 0; ks < PD; ++ks) { ka[ks] = lds_rd16(st + KOFF0(ks) + lane * 16); kb[ks] = lds_rd16(st + KOFF1(ks) + lane * 16); }
.LBB0_1171:
	s_waitcnt vmcnt(0)
	s_bitcmp1_b32 s8, 0
	s_cselect_b32 s70, 0xa000, 0
	v_add_u32_e32 v0, s70, v176
	s_add_i32 s72, s8, 1
	s_cmp_ge_u32 s72, s78
	s_mov_b64 s[0:1], -1
	s_waitcnt lgkmcnt(0)
	s_barrier
	ds_read_b128 v[2:5], v0
	ds_read_b128 v[6:9], v0 offset:1024
	ds_read_b128 v[12:15], v0 offset:8192
	ds_read_b128 v[226:229], v0 offset:9216
	ds_read_b128 v[230:233], v0 offset:2048
	ds_read_b128 v[234:237], v0 offset:3072
	ds_read_b128 v[238:241], v0 offset:10240
	ds_read_b128 v[242:245], v0 offset:11264
	s_cbranch_scc1 .LBB0_1174
	s_andn2_b64 vcc, exec, s[0:1]
	s_cbranch_vccz .LBB0_1177

; __device__ __forceinline__ void attn_phase(const Ptrs& P, LAS unsigned char* lds, int vcu) {
;     ...
;             asm volatile("s_waitcnt vmcnt(0)" ::: "memory");
;             __syncthreads();
;             if (t + 1 < NT) ISSUE_TILE(t + 1, (t + 1) & 1); else if (ui + 1 < 4) ISSUE_TILE(0, 0);
;             if (64 * t <= qw) {
.LBB0_1177:
	s_lshl_b32 s6, s72, 14
	s_lshl_b32 s7, s72, 13
	s_mov_b32 s1, 0
	s_bitcmp1_b32 s72, 0
	s_cselect_b32 s9, 0xa000, 0
	s_bitcmp1_b32 s32, 0
	s_cselect_b32 s0, s7, s6
	s_add_i32 m0, s9, s33
	v_lshl_add_u64 v[250:251], v[192:193], 0, s[0:1]
	global_load_lds_dwordx4 v[250:251], off
	s_bitcmp1_b32 s32, 1
	s_cselect_b32 s0, s7, s6
	s_add_i32 m0, s9, s93
	v_lshl_add_u64 v[252:253], v[194:195], 0, s[0:1]
	global_load_lds_dwordx4 v[252:253], off
	s_bitcmp1_b32 s32, 2
	s_cselect_b32 s0, s7, s6
	s_add_i32 m0, s9, s91
	v_lshl_add_u64 v[250:251], v[196:197], 0, s[0:1]
	global_load_lds_dwordx4 v[250:251], off
	s_bitcmp1_b32 s32, 3
	s_cselect_b32 s0, s7, s6
	s_add_i32 m0, s9, s71
	v_lshl_add_u64 v[250:251], v[198:199], 0, s[0:1]
	global_load_lds_dwordx4 v[250:251], off
	s_bitcmp1_b32 s32, 4
	s_cselect_b32 s0, s7, s6
	s_add_i32 m0, s9, s75
	v_lshl_add_u64 v[252:253], v[202:203], 0, s[0:1]
	global_load_lds_dwordx4 v[252:253], off
	s_sub_i32 s0, s90, 63
	s_cmp_gt_u32 s0, s92
	s_cbranch_scc1 .LBB0_1229
; __device__ __forceinline__ void attn_phase(const Ptrs& P, LAS unsigned char* lds, int vcu) {
;     ...
;                 { constexpr int PD = 4;
;                   bf16x8 ka[12], kb[12];
; #pragma unroll
;                   for (int ks = 0; ks < PD; ++ks) { ka[ks] = lds_rd16(st + KOFF0(ks) + lane * 16); kb[ks] = lds_rd16(st + KOFF1(ks) + lane * 16); }
;                   __builtin_amdgcn_sched_barrier(0);
; #pragma unroll
;                   for (int ks = 0; ks < 12; ++ks) {
;                       if (ks + PD < 12) { ka[ks + PD] = lds_rd16(st + KOFF0(ks + PD) + lane * 16); kb[ks + PD] = lds_rd16(st + KOFF1(ks + PD) + lane * 16); }
;                       p0 = __builtin_amdgcn_mfma_f32_32x32x16_bf16(ka[ks], qf[ks], ks == 0 ? negmv : p0, 0, 0, 0);
;                       p1 = __builtin_amdgcn_mfma_f32_32x32x16_bf16(kb[ks], qf[ks], ks == 0 ? negmv : p1, 0, 0, 0);
;                       __builtin_amdgcn_sched_barrier(0);
;                   } }
;     ...
;                 if (64 * t + 63 > qw) {
;                     const int qa = qw + r32 - 64 * t - 4 * hi;
; #pragma unroll
;                     for (int i = 0; i < 16; ++i) { const int kv = (i & 3) + 8 * (i >> 2); if (kv > qa) p0[i] = -INFINITY; if (kv + 32 > qa) p1[i] = -INFINITY; }
;                 }
.LBB0_1218:
	s_waitcnt lgkmcnt(0)
	v_mfma_f32_32x32x16_bf16 v[112:127], v[2:5], v[128:131], v[80:95]
	ds_read_b128 v[2:5], v0 offset:4096
	ds_read_b128 v[246:249], v0 offset:12288
	v_mfma_f32_32x32x16_bf16 v[96:111], v[12:15], v[128:131], v[80:95]
	v_mfma_f32_32x32x16_bf16 v[112:127], v[6:9], v[132:135], v[112:127]
	ds_read_b128 v[6:9], v0 offset:5120
	ds_read_b128 v[12:15], v0 offset:13312
	v_mfma_f32_32x32x16_bf16 v[96:111], v[226:229], v[132:135], v[96:111]
	v_mfma_f32_32x32x16_bf16 v[112:127], v[230:233], v[136:139], v[112:127]
	ds_read_b128 v[226:229], v0 offset:6144
	ds_read_b128 v[230:233], v0 offset:14336
	v_mfma_f32_32x32x16_bf16 v[96:111], v[238:241], v[136:139], v[96:111]
	v_mfma_f32_32x32x16_bf16 v[112:127], v[234:237], v[140:143], v[112:127]
	ds_read_b128 v[234:237], v0 offset:7168
	ds_read_b128 v[238:241], v0 offset:15360
	v_mfma_f32_32x32x16_bf16 v[96:111], v[242:245], v[140:143], v[96:111]
	s_waitcnt lgkmcnt(0)
	v_mfma_f32_32x32x16_bf16 v[112:127], v[2:5], v[148:151], v[112:127]
	ds_read_b128 v[2:5], v0 offset:16384
	ds_read_b128 v[242:245], v0 offset:20480
	v_mfma_f32_32x32x16_bf16 v[96:111], v[246:249], v[148:151], v[96:111]
	v_mfma_f32_32x32x16_bf16 v[112:127], v[6:9], v[144:147], v[112:127]
	ds_read_b128 v[6:9], v0 offset:17408
	ds_read_b128 v[246:249], v0 offset:21504
	v_mfma_f32_32x32x16_bf16 v[96:111], v[12:15], v[144:147], v[96:111]
	v_mfma_f32_32x32x16_bf16 v[112:127], v[226:229], v[152:155], v[112:127]
	ds_read_b128 v[12:15], v0 offset:18432
	ds_read_b128 v[226:229], v0 offset:22528
	v_mfma_f32_32x32x16_bf16 v[96:111], v[230:233], v[152:155], v[96:111]
	v_mfma_f32_32x32x16_bf16 v[112:127], v[234:237], v[156:159], v[112:127]
	ds_read_b128 v[230:233], v0 offset:19456
	ds_read_b128 v[234:237], v0 offset:23552
	v_mfma_f32_32x32x16_bf16 v[96:111], v[238:241], v[156:159], v[96:111]
	s_waitcnt lgkmcnt(0)
	v_mfma_f32_32x32x16_bf16 v[112:127], v[2:5], v[160:163], v[112:127]
	v_mfma_f32_32x32x16_bf16 v[96:111], v[242:245], v[160:163], v[96:111]
	v_mfma_f32_32x32x16_bf16 v[112:127], v[6:9], v[164:167], v[112:127]
	v_mfma_f32_32x32x16_bf16 v[96:111], v[246:249], v[164:167], v[96:111]
	v_mfma_f32_32x32x16_bf16 v[112:127], v[12:15], v[168:171], v[112:127]
	v_mfma_f32_32x32x16_bf16 v[96:111], v[226:229], v[168:171], v[96:111]
	v_mfma_f32_32x32x16_bf16 v[112:127], v[230:233], v[172:175], v[112:127]
	v_mfma_f32_32x32x16_bf16 v[96:111], v[234:237], v[172:175], v[96:111]
	s_cmp_le_u32 s90, s92
	s_cbranch_scc1 .LBB0_1220
	v_cmp_gt_i32_e64 s[64:65], 26, v223
	v_cmp_gt_i32_e64 s[66:67], 27, v223
	v_cmp_gt_i32_e64 s[62:63], 25, v223
	s_and_b64 s[64:65], s[66:67], s[64:65]
	v_cmp_gt_i32_e64 s[60:61], 24, v223
	s_and_b64 s[62:63], s[64:65], s[62:63]
	v_cmp_gt_i32_e64 s[58:59], 19, v223
	s_and_b64 s[60:61], s[62:63], s[60:61]
	v_cmp_gt_i32_e64 s[56:57], 18, v223
	s_and_b64 s[58:59], s[60:61], s[58:59]
	v_cmp_gt_i32_e64 s[54:55], 17, v223
	s_and_b64 s[56:57], s[58:59], s[56:57]
	v_cmp_gt_i32_e64 s[52:53], 16, v223
	s_and_b64 s[54:55], s[56:57], s[54:55]
	v_cmp_gt_i32_e64 s[50:51], 11, v223
	s_and_b64 s[52:53], s[54:55], s[52:53]
	v_cmp_gt_i32_e64 s[48:49], 10, v223
	s_and_b64 s[50:51], s[52:53], s[50:51]
	v_cmp_gt_i32_e64 s[46:47], 9, v223
	s_and_b64 s[48:49], s[50:51], s[48:49]
	v_cmp_gt_i32_e64 s[44:45], 8, v223
	s_and_b64 s[46:47], s[48:49], s[46:47]
	v_cmp_gt_i32_e64 s[42:43], 3, v223
	s_and_b64 s[44:45], s[46:47], s[44:45]
	v_cmp_gt_i32_e64 s[40:41], 2, v223
	s_and_b64 s[42:43], s[44:45], s[42:43]
	v_cmp_gt_i32_e64 s[38:39], 1, v223
	s_and_b64 s[40:41], s[42:43], s[40:41]
	v_cmp_gt_i32_e64 s[36:37], 0, v223
	s_and_b64 s[38:39], s[40:41], s[38:39]
	s_and_b64 s[36:37], s[38:39], s[36:37]
	v_cmp_gt_i32_e64 s[34:35], 58, v223
	v_cndmask_b32_e64 v112, v112, v220, s[36:37]
	v_cmp_gt_i32_e64 s[36:37], 59, v223
	v_cmp_gt_i32_e64 s[30:31], 57, v223
	s_and_b64 s[34:35], s[36:37], s[34:35]
	v_cmp_gt_i32_e64 s[28:29], 56, v223
	s_and_b64 s[30:31], s[34:35], s[30:31]
	v_cmp_gt_i32_e64 s[26:27], 51, v223
	s_and_b64 s[28:29], s[30:31], s[28:29]
	v_cmp_gt_i32_e64 s[24:25], 50, v223
	s_and_b64 s[26:27], s[28:29], s[26:27]
	v_cmp_gt_i32_e64 s[22:23], 49, v223
	s_and_b64 s[24:25], s[26:27], s[24:25]
	v_cmp_gt_i32_e64 s[20:21], 48, v223
	s_and_b64 s[22:23], s[24:25], s[22:23]
	v_cmp_gt_i32_e64 s[18:19], 43, v223
	s_and_b64 s[20:21], s[22:23], s[20:21]
	v_cmp_gt_i32_e64 s[16:17], 42, v223
	s_and_b64 s[18:19], s[20:21], s[18:19]
	v_cmp_gt_i32_e64 s[14:15], 41, v223
	s_and_b64 s[16:17], s[18:19], s[16:17]
	v_cmp_gt_i32_e64 s[12:13], 40, v223
	s_and_b64 s[14:15], s[16:17], s[14:15]
	v_cmp_gt_i32_e64 s[8:9], 35, v223
	s_and_b64 s[12:13], s[14:15], s[12:13]
	v_cmp_gt_i32_e64 s[6:7], 34, v223
	s_and_b64 s[8:9], s[12:13], s[8:9]
	v_cmp_gt_i32_e64 s[0:1], 33, v223
	s_and_b64 s[6:7], s[8:9], s[6:7]
	v_cmp_gt_i32_e32 vcc, 32, v223
	s_and_b64 s[0:1], s[6:7], s[0:1]
	v_cndmask_b32_e64 v125, v125, v220, s[62:63]
	v_cndmask_b32_e64 v124, v124, v220, s[60:61]
	v_cndmask_b32_e64 v123, v123, v220, s[58:59]
	v_cndmask_b32_e64 v122, v122, v220, s[56:57]
	v_cndmask_b32_e64 v121, v121, v220, s[54:55]
	v_cndmask_b32_e64 v120, v120, v220, s[52:53]
	v_cndmask_b32_e64 v119, v119, v220, s[50:51]
	v_cndmask_b32_e64 v118, v118, v220, s[48:49]
	v_readlane_b32 s48, v254, 23
	s_and_b64 vcc, s[0:1], vcc
	v_cndmask_b32_e64 v127, v127, v220, s[66:67]
	v_cndmask_b32_e64 v126, v126, v220, s[64:65]
	v_readlane_b32 s49, v254, 24
	v_cndmask_b32_e64 v117, v117, v220, s[46:47]
	v_cndmask_b32_e64 v116, v116, v220, s[44:45]
	v_cndmask_b32_e64 v115, v115, v220, s[42:43]
	v_cndmask_b32_e64 v114, v114, v220, s[40:41]
	v_cndmask_b32_e64 v113, v113, v220, s[38:39]
	v_cndmask_b32_e64 v111, v111, v220, s[36:37]
	v_cndmask_b32_e64 v110, v110, v220, s[34:35]
	v_cndmask_b32_e64 v109, v109, v220, s[30:31]
	v_cndmask_b32_e64 v108, v108, v220, s[28:29]
	v_cndmask_b32_e64 v107, v107, v220, s[26:27]
	v_cndmask_b32_e64 v106, v106, v220, s[24:25]
	v_cndmask_b32_e64 v105, v105, v220, s[22:23]
	v_cndmask_b32_e64 v104, v104, v220, s[20:21]
	v_cndmask_b32_e64 v103, v103, v220, s[18:19]
	v_cndmask_b32_e64 v102, v102, v220, s[16:17]
	v_cndmask_b32_e64 v101, v101, v220, s[14:15]
	v_cndmask_b32_e64 v100, v100, v220, s[12:13]
	v_cndmask_b32_e64 v99, v99, v220, s[8:9]
	v_cndmask_b32_e64 v98, v98, v220, s[6:7]
	v_cndmask_b32_e64 v97, v97, v220, s[0:1]
	v_cndmask_b32_e32 v96, v96, v220, vcc
	v_readlane_b32 s50, v254, 25
	v_readlane_b32 s51, v254, 26
	v_readlane_b32 s52, v254, 27
	v_readlane_b32 s53, v254, 28
	v_readlane_b32 s54, v254, 29
	v_readlane_b32 s55, v254, 30
	v_readlane_b32 s56, v254, 31
	v_readlane_b32 s57, v254, 32
	v_readlane_b32 s58, v254, 33
	v_readlane_b32 s59, v254, 34
	v_readlane_b32 s60, v254, 35
	v_readlane_b32 s61, v254, 36
	v_readlane_b32 s62, v254, 37
	v_readlane_b32 s63, v254, 38
